# hy_tr channel loop: conv weights via v_readlane instead of 4 ds_bpermute + waits per channel; tile reads of 8 channels batched
# baseline (speedup 1.0000x reference)
; __device__ __forceinline__ bf16_t f2bf(float f) { return (bf16_t)(cvt_pk_bf16(f, 0.f) & 0xffffu); }
; __device__ __forceinline__ float bf2f(bf16_t b) { return __uint_as_float(((unsigned)b) << 16); }
; __device__ __forceinline__ void hy_tr_item(const Ctx& C, int l, int item) {
;     ...
;     const float w0v = C.P->in[12][(l * 3 + 0) * 768 + cb * 64 + lane], w1v = C.P->in[12][(l * 3 + 1) * 768 + cb * 64 + lane], w2v = C.P->in[12][(l * 3 + 2) * 768 + cb * 64 + lane], bbv = C.P->in[13][l * 768 + cb * 64 + lane];
; #pragma unroll 8
;     for (int ch = 0; ch < 64; ++ch) { const int cch = cb * 64 + ch;
;         const float w0 = __shfl(w0v, ch), w1 = __shfl(w1v, ch), w2 = __shfl(w2v, ch), bb = __shfl(bbv, ch);
;         const float v = bb + w0 * bf2f(tile[lane * 66 + ch]) + w1 * bf2f(tile[(lane + 1) * 66 + ch]) + w2 * bf2f(tile[(lane + 2) * 66 + ch]);
;         uct[(size_t)cch * M_TOK + tok0 + lane] = f2bf(v); }
.LBB0_488:
	s_lshr_b32 s5, s0, 16
	ds_read2_b32 v[8:9], v23 offset1:1
	ds_read2_b32 v[10:11], v23 offset0:2 offset1:3
	ds_read2_b32 v[12:13], v23 offset0:33 offset1:34
	ds_read2_b32 v[24:25], v23 offset0:35 offset1:36
	ds_read2_b32 v[26:27], v23 offset0:66 offset1:67
	ds_read2_b32 v[28:29], v23 offset0:68 offset1:69
	s_add_i32 s6, s5, 1
	s_add_i32 s7, s5, 2
	s_add_i32 s9, s5, 3
	s_add_i32 s10, s5, 4
	s_add_i32 s11, s5, 5
	s_add_i32 s12, s5, 6
	s_add_i32 s13, s5, 7
	s_add_u32 s42, s0, 0x17000000
	s_addc_u32 s43, s1, 0
	v_readlane_b32 s68, v18, s5
	v_readlane_b32 s76, v19, s5
	v_readlane_b32 s84, v20, s5
	v_readlane_b32 s92, v21, s5
	v_readlane_b32 s69, v18, s6
	v_readlane_b32 s77, v19, s6
	v_readlane_b32 s85, v20, s6
	v_readlane_b32 s93, v21, s6
	v_readlane_b32 s70, v18, s7
	v_readlane_b32 s78, v19, s7
	v_readlane_b32 s86, v20, s7
	v_readlane_b32 s94, v21, s7
	v_readlane_b32 s71, v18, s9
	v_readlane_b32 s79, v19, s9
	v_readlane_b32 s87, v20, s9
	v_readlane_b32 s95, v21, s9
	v_readlane_b32 s72, v18, s10
	v_readlane_b32 s80, v19, s10
	v_readlane_b32 s88, v20, s10
	v_readlane_b32 s96, v21, s10
	v_readlane_b32 s73, v18, s11
	v_readlane_b32 s81, v19, s11
	v_readlane_b32 s89, v20, s11
	v_readlane_b32 s97, v21, s11
	v_readlane_b32 s74, v18, s12
	v_readlane_b32 s82, v19, s12
	v_readlane_b32 s90, v20, s12
	v_readlane_b32 s98, v21, s12
	v_readlane_b32 s75, v18, s13
	v_readlane_b32 s83, v19, s13
	v_readlane_b32 s91, v20, s13
	v_readlane_b32 s99, v21, s13
	s_waitcnt lgkmcnt(0)
	v_lshlrev_b32_e32 v30, 16, v8
	v_lshlrev_b32_e32 v31, 16, v12
	v_lshlrev_b32_e32 v32, 16, v26
	v_mov_b32_e32 v33, s92
	v_fmac_f32_e32 v33, s68, v30
	v_fmac_f32_e32 v33, s76, v31
	v_fmac_f32_e32 v33, s84, v32
	v_lshl_add_u64 v[34:35], v[4:5], 0, s[42:43]
	v_cvt_pk_bf16_f32 v33, v33, v33
	s_add_u32 s42, s42, 0x10000
	s_addc_u32 s43, s43, 0
	global_store_short v[34:35], v33, off
	v_and_b32_e32 v30, 0xffff0000, v8
	v_and_b32_e32 v31, 0xffff0000, v12
	v_and_b32_e32 v32, 0xffff0000, v26
	v_mov_b32_e32 v33, s93
	v_fmac_f32_e32 v33, s69, v30
	v_fmac_f32_e32 v33, s77, v31
	v_fmac_f32_e32 v33, s85, v32
	v_lshl_add_u64 v[34:35], v[4:5], 0, s[42:43]
	v_cvt_pk_bf16_f32 v33, v33, v33
	s_add_u32 s42, s42, 0x10000
	s_addc_u32 s43, s43, 0
	global_store_short v[34:35], v33, off
	v_lshlrev_b32_e32 v30, 16, v9
	v_lshlrev_b32_e32 v31, 16, v13
	v_lshlrev_b32_e32 v32, 16, v27
	v_mov_b32_e32 v33, s94
	v_fmac_f32_e32 v33, s70, v30
	v_fmac_f32_e32 v33, s78, v31
	v_fmac_f32_e32 v33, s86, v32
	v_lshl_add_u64 v[34:35], v[4:5], 0, s[42:43]
	v_cvt_pk_bf16_f32 v33, v33, v33
	s_add_u32 s42, s42, 0x10000
	s_addc_u32 s43, s43, 0
	global_store_short v[34:35], v33, off
	v_and_b32_e32 v30, 0xffff0000, v9
	v_and_b32_e32 v31, 0xffff0000, v13
	v_and_b32_e32 v32, 0xffff0000, v27
	v_mov_b32_e32 v33, s95
	v_fmac_f32_e32 v33, s71, v30
	v_fmac_f32_e32 v33, s79, v31
	v_fmac_f32_e32 v33, s87, v32
	v_lshl_add_u64 v[34:35], v[4:5], 0, s[42:43]
	v_cvt_pk_bf16_f32 v33, v33, v33
	s_add_u32 s42, s42, 0x10000
	s_addc_u32 s43, s43, 0
	global_store_short v[34:35], v33, off
	v_lshlrev_b32_e32 v30, 16, v10
	v_lshlrev_b32_e32 v31, 16, v24
	v_lshlrev_b32_e32 v32, 16, v28
	v_mov_b32_e32 v33, s96
	v_fmac_f32_e32 v33, s72, v30
	v_fmac_f32_e32 v33, s80, v31
	v_fmac_f32_e32 v33, s88, v32
	v_lshl_add_u64 v[34:35], v[4:5], 0, s[42:43]
	v_cvt_pk_bf16_f32 v33, v33, v33
	s_add_u32 s42, s42, 0x10000
	s_addc_u32 s43, s43, 0
	global_store_short v[34:35], v33, off
	v_and_b32_e32 v30, 0xffff0000, v10
	v_and_b32_e32 v31, 0xffff0000, v24
	v_and_b32_e32 v32, 0xffff0000, v28
	v_mov_b32_e32 v33, s97
	v_fmac_f32_e32 v33, s73, v30
	v_fmac_f32_e32 v33, s81, v31
	v_fmac_f32_e32 v33, s89, v32
	v_lshl_add_u64 v[34:35], v[4:5], 0, s[42:43]
	v_cvt_pk_bf16_f32 v33, v33, v33
	s_add_u32 s42, s42, 0x10000
	s_addc_u32 s43, s43, 0
	global_store_short v[34:35], v33, off
	v_lshlrev_b32_e32 v30, 16, v11
	v_lshlrev_b32_e32 v31, 16, v25
	v_lshlrev_b32_e32 v32, 16, v29
	v_mov_b32_e32 v33, s98
	v_fmac_f32_e32 v33, s74, v30
	v_fmac_f32_e32 v33, s82, v31
	v_fmac_f32_e32 v33, s90, v32
	v_lshl_add_u64 v[34:35], v[4:5], 0, s[42:43]
	v_cvt_pk_bf16_f32 v33, v33, v33
	s_add_u32 s42, s42, 0x10000
	s_addc_u32 s43, s43, 0
	global_store_short v[34:35], v33, off
	v_and_b32_e32 v30, 0xffff0000, v11
	v_and_b32_e32 v31, 0xffff0000, v25
	v_and_b32_e32 v32, 0xffff0000, v29
	v_mov_b32_e32 v33, s99
	v_fmac_f32_e32 v33, s75, v30
	v_fmac_f32_e32 v33, s83, v31
	v_fmac_f32_e32 v33, s91, v32
	v_lshl_add_u64 v[34:35], v[4:5], 0, s[42:43]
	v_cvt_pk_bf16_f32 v33, v33, v33
	global_store_short v[34:35], v33, off
	s_add_u32 s0, s0, 0x80000
	s_addc_u32 s1, s1, 0
	v_add_u32_e32 v23, 16, v23
	s_cmp_lg_u32 s0, 0x400000
	s_cbranch_scc1 .LBB0_488
	v_readlane_b32 s0, v254, 20
	s_waitcnt lgkmcnt(0)
	s_add_i32 s8, s8, s0
	s_cmpk_gt_i32 s8, 0x17ff
	v_readlane_b32 s22, v253, 26
	v_readlane_b32 s1, v254, 21
	s_cbranch_scc0 .LBB0_481
